# EpiSwiglu epilogue rewritten by hand (ssq loads hoisted, transcendental chains interleaved 8-wide, one 16B store per row) on top of Scale epilogue + mLSTM staging fixes
# speedup vs baseline: 1.0270x; 1.0255x over previous
;     __device__ __forceinline__ void operator()(const f32x4 (&acc)[2][2][4][2], const Unit& u, int wr, int wc, int fr, int fq) const {
;         const int row0 = u.pm * BM + wr * 64 + fr, col0 = u.pn * HALF + wc * 32 + 8 * fq;
; #pragma unroll
;         for (int ai = 0; ai < 2; ++ai)
; #pragma unroll
;             for (int m = 0; m < 4; ++m) { const int row = row0 + ai * HALF + m * 16; const f32x4 q0 = *(const f32x4*)(ssq + (size_t)row * 16), q1 = *(const f32x4*)(ssq + (size_t)row * 16 + 4), q2 = *(const f32x4*)(ssq + (size_t)row * 16 + 8), q3 = *(const f32x4*)(ssq + (size_t)row * 16 + 12);
;                 const float rs = rsqrtf(((((q0[0] + q0[1]) + (q0[2] + q0[3])) + ((q1[0] + q1[1]) + (q1[2] + q1[3]))) + (((q2[0] + q2[1]) + (q2[2] + q2[3])) + ((q3[0] + q3[1]) + (q3[2] + q3[3])))) * (1.0f / 1024.0f) + 1e-6f);
;                 float a[8];
; #pragma unroll
;                 for (int n = 0; n < 2; ++n)
; #pragma unroll
;                     for (int j = 0; j < 4; ++j) { const float g = acc[ai][0][m][n][j] * rs, up = acc[ai][1][m][n][j] * rs; a[4 * n + j] = g * up * __builtin_amdgcn_rcpf(1.0f + __expf(-g)); }
.LBB0_610:
	v_readlane_b32 s28, v253, 45
	v_readlane_b32 s29, v253, 46
	v_lshl_add_u32 v192, s55, 8, v147
	v_and_b32_e32 v193, 24, v149
	v_lshlrev_b32_e32 v193, 1, v193
	v_lshl_add_u32 v193, v192, 6, v193
	v_add_u32_e32 v230, 0x2000, v193
	global_load_dwordx4 v[152:155], v193, s[16:17]
	global_load_dwordx4 v[156:159], v193, s[16:17] offset:1024
	global_load_dwordx4 v[160:163], v193, s[16:17] offset:2048
	global_load_dwordx4 v[164:167], v193, s[16:17] offset:3072
	global_load_dwordx4 v[168:171], v230, s[16:17]
	global_load_dwordx4 v[172:175], v230, s[16:17] offset:1024
	global_load_dwordx4 v[176:179], v230, s[16:17] offset:2048
	global_load_dwordx4 v[180:183], v230, s[16:17] offset:3072
	v_xor_b32_e32 v228, 16, v214
	v_lshlrev_b32_e32 v228, 2, v228
	v_xor_b32_e32 v229, 32, v214
	v_lshlrev_b32_e32 v229, 2, v229
	s_movk_i32 s21, 0x1600
	v_lshl_or_b32 v231, s54, 7, v149
	v_lshlrev_b32_e32 v231, 1, v231
	v_mad_u32_u24 v184, v192, s21, v231
	v_add_u32_e32 v185, 0x16000, v184
	v_add_u32_e32 v186, 0x16000, v185
	v_add_u32_e32 v187, 0x16000, v186
	v_add_u32_e32 v188, 0xb0000, v184
	v_add_u32_e32 v189, 0xb0000, v185
	v_add_u32_e32 v190, 0xb0000, v186
	v_add_u32_e32 v191, 0xb0000, v187
	s_waitcnt vmcnt(7)
	v_add_f32_e32 v154, v154, v155
	v_add_f32_e32 v194, v152, v153
	v_add_f32_e32 v194, v194, v154
	s_waitcnt vmcnt(6)
	v_add_f32_e32 v158, v158, v159
	v_add_f32_e32 v195, v156, v157
	v_add_f32_e32 v195, v195, v158
	s_waitcnt vmcnt(5)
	v_add_f32_e32 v162, v162, v163
	v_add_f32_e32 v196, v160, v161
	v_add_f32_e32 v196, v196, v162
	s_waitcnt vmcnt(4)
	v_add_f32_e32 v166, v166, v167
	v_add_f32_e32 v197, v164, v165
	v_add_f32_e32 v197, v197, v166
	s_waitcnt vmcnt(3)
	v_add_f32_e32 v170, v170, v171
	v_add_f32_e32 v204, v168, v169
	v_add_f32_e32 v204, v204, v170
	s_waitcnt vmcnt(2)
	v_add_f32_e32 v174, v174, v175
	v_add_f32_e32 v205, v172, v173
	v_add_f32_e32 v205, v205, v174
	s_waitcnt vmcnt(1)
	v_add_f32_e32 v178, v178, v179
	v_add_f32_e32 v206, v176, v177
	v_add_f32_e32 v206, v206, v178
	s_waitcnt vmcnt(0)
	v_add_f32_e32 v182, v182, v183
	v_add_f32_e32 v207, v180, v181
	v_add_f32_e32 v207, v207, v182
	ds_bpermute_b32 v220, v228, v194
	ds_bpermute_b32 v221, v228, v195
	ds_bpermute_b32 v222, v228, v196
	ds_bpermute_b32 v223, v228, v197
	ds_bpermute_b32 v224, v228, v204
	ds_bpermute_b32 v225, v228, v205
	ds_bpermute_b32 v226, v228, v206
	ds_bpermute_b32 v227, v228, v207
	s_waitcnt lgkmcnt(7)
	v_add_f32_e32 v194, v194, v220
	s_waitcnt lgkmcnt(6)
	v_add_f32_e32 v195, v195, v221
	s_waitcnt lgkmcnt(5)
	v_add_f32_e32 v196, v196, v222
	s_waitcnt lgkmcnt(4)
	v_add_f32_e32 v197, v197, v223
	s_waitcnt lgkmcnt(3)
	v_add_f32_e32 v204, v204, v224
	s_waitcnt lgkmcnt(2)
	v_add_f32_e32 v205, v205, v225
	s_waitcnt lgkmcnt(1)
	v_add_f32_e32 v206, v206, v226
	s_waitcnt lgkmcnt(0)
	v_add_f32_e32 v207, v207, v227
	ds_bpermute_b32 v220, v229, v194
	ds_bpermute_b32 v221, v229, v195
	ds_bpermute_b32 v222, v229, v196
	ds_bpermute_b32 v223, v229, v197
	ds_bpermute_b32 v224, v229, v204
	ds_bpermute_b32 v225, v229, v205
	ds_bpermute_b32 v226, v229, v206
	ds_bpermute_b32 v227, v229, v207
	s_waitcnt lgkmcnt(7)
	v_add_f32_e32 v194, v194, v220
	s_waitcnt lgkmcnt(6)
	v_add_f32_e32 v195, v195, v221
	s_waitcnt lgkmcnt(5)
	v_add_f32_e32 v196, v196, v222
	s_waitcnt lgkmcnt(4)
	v_add_f32_e32 v197, v197, v223
	s_waitcnt lgkmcnt(3)
	v_add_f32_e32 v204, v204, v224
	s_waitcnt lgkmcnt(2)
	v_add_f32_e32 v205, v205, v225
	s_waitcnt lgkmcnt(1)
	v_add_f32_e32 v206, v206, v226
	s_waitcnt lgkmcnt(0)
	v_add_f32_e32 v207, v207, v227
	v_fmamk_f32 v194, v194, 0x3a800000, v208
	v_fmamk_f32 v195, v195, 0x3a800000, v208
	v_fmamk_f32 v196, v196, 0x3a800000, v208
	v_fmamk_f32 v197, v197, 0x3a800000, v208
	v_fmamk_f32 v204, v204, 0x3a800000, v208
	v_fmamk_f32 v205, v205, 0x3a800000, v208
	v_fmamk_f32 v206, v206, 0x3a800000, v208
	v_fmamk_f32 v207, v207, 0x3a800000, v208
	v_rsq_f32_e32 v152, v194
	v_rsq_f32_e32 v156, v195
	v_rsq_f32_e32 v160, v196
	v_rsq_f32_e32 v164, v197
	v_rsq_f32_e32 v168, v204
	v_rsq_f32_e32 v172, v205
	v_rsq_f32_e32 v176, v206
	v_rsq_f32_e32 v180, v207
	v_pk_mul_f32 v[128:129], v[128:129], v[152:153] op_sel_hi:[1,0]
	v_pk_mul_f32 v[130:131], v[130:131], v[152:153] op_sel_hi:[1,0]
	v_pk_mul_f32 v[120:121], v[120:121], v[152:153] op_sel_hi:[1,0]
	v_pk_mul_f32 v[122:123], v[122:123], v[152:153] op_sel_hi:[1,0]
	v_pk_mul_f32 v[124:125], v[124:125], v[152:153] op_sel_hi:[1,0]
	v_pk_mul_f32 v[126:127], v[126:127], v[152:153] op_sel_hi:[1,0]
	v_pk_mul_f32 v[116:117], v[116:117], v[152:153] op_sel_hi:[1,0]
	v_pk_mul_f32 v[118:119], v[118:119], v[152:153] op_sel_hi:[1,0]
	v_mul_f32_e32 v124, v128, v124
	v_mul_f32_e32 v125, v129, v125
	v_mul_f32_e32 v126, v130, v126
	v_mul_f32_e32 v127, v131, v127
	v_mul_f32_e32 v116, v120, v116
	v_mul_f32_e32 v117, v121, v117
	v_mul_f32_e32 v118, v122, v118
	v_mul_f32_e32 v119, v123, v119
	v_mul_f32_e32 v128, 0xbfb8aa3b, v128
	v_mul_f32_e32 v129, 0xbfb8aa3b, v129
	v_mul_f32_e32 v130, 0xbfb8aa3b, v130
	v_mul_f32_e32 v131, 0xbfb8aa3b, v131
	v_mul_f32_e32 v120, 0xbfb8aa3b, v120
	v_mul_f32_e32 v121, 0xbfb8aa3b, v121
	v_mul_f32_e32 v122, 0xbfb8aa3b, v122
	v_mul_f32_e32 v123, 0xbfb8aa3b, v123
	v_exp_f32_e32 v128, v128
	v_exp_f32_e32 v129, v129
	v_exp_f32_e32 v130, v130
	v_exp_f32_e32 v131, v131
	v_exp_f32_e32 v120, v120
	v_exp_f32_e32 v121, v121
	v_exp_f32_e32 v122, v122
	v_exp_f32_e32 v123, v123
	v_add_f32_e32 v128, 1.0, v128
	v_add_f32_e32 v129, 1.0, v129
	v_add_f32_e32 v130, 1.0, v130
	v_add_f32_e32 v131, 1.0, v131
	v_add_f32_e32 v120, 1.0, v120
	v_add_f32_e32 v121, 1.0, v121
	v_add_f32_e32 v122, 1.0, v122
	v_add_f32_e32 v123, 1.0, v123
	v_rcp_f32_e32 v128, v128
; __device__ __forceinline__ unsigned cvt_pk_bf16(float lo, float hi) { unsigned r; asm volatile("v_cvt_pk_bf16_f32 %0, %1, %2" : "=v"(r) : "v"(lo), "v"(hi)); return r; }
;     __device__ __forceinline__ void operator()(const f32x4 (&acc)[2][2][4][2], const Unit& u, int wr, int wc, int fr, int fq) const {
;     ...
;             for (int m = 0; m < 4; ++m) { const int row = row0 + ai * HALF + m * 16; const f32x4 q0 = *(const f32x4*)(ssq + (size_t)row * 16), q1 = *(const f32x4*)(ssq + (size_t)row * 16 + 4), q2 = *(const f32x4*)(ssq + (size_t)row * 16 + 8), q3 = *(const f32x4*)(ssq + (size_t)row * 16 + 12);
;                 const float rs = rsqrtf(((((q0[0] + q0[1]) + (q0[2] + q0[3])) + ((q1[0] + q1[1]) + (q1[2] + q1[3]))) + (((q2[0] + q2[1]) + (q2[2] + q2[3])) + ((q3[0] + q3[1]) + (q3[2] + q3[3])))) * (1.0f / 1024.0f) + 1e-6f);
;                 float a[8];
; #pragma unroll
;                 for (int n = 0; n < 2; ++n)
; #pragma unroll
;                     for (int j = 0; j < 4; ++j) { const float g = acc[ai][0][m][n][j] * rs, up = acc[ai][1][m][n][j] * rs; a[4 * n + j] = g * up * __builtin_amdgcn_rcpf(1.0f + __expf(-g)); }
;                 u32x4 w; w.x = cvt_pk_bf16(a[0], a[1]); w.y = cvt_pk_bf16(a[2], a[3]); w.z = cvt_pk_bf16(a[4], a[5]); w.w = cvt_pk_bf16(a[6], a[7]);
;                 *(u32x4*)(O + (size_t)row * ldc + col0) = w; }
	v_rcp_f32_e32 v129, v129
	v_rcp_f32_e32 v130, v130
	v_rcp_f32_e32 v131, v131
	v_rcp_f32_e32 v120, v120
	v_rcp_f32_e32 v121, v121
	v_rcp_f32_e32 v122, v122
	v_rcp_f32_e32 v123, v123
	v_mul_f32_e32 v128, v124, v128
	v_mul_f32_e32 v129, v125, v129
	v_mul_f32_e32 v130, v126, v130
	v_mul_f32_e32 v131, v127, v131
	v_mul_f32_e32 v120, v116, v120
	v_mul_f32_e32 v121, v117, v121
	v_mul_f32_e32 v122, v118, v122
	v_mul_f32_e32 v123, v119, v123
	v_cvt_pk_bf16_f32 v128, v128, v129
	v_cvt_pk_bf16_f32 v129, v130, v131
	v_cvt_pk_bf16_f32 v130, v120, v121
	v_cvt_pk_bf16_f32 v131, v122, v123
	global_store_dwordx4 v184, v[128:131], s[28:29]
	v_pk_mul_f32 v[112:113], v[112:113], v[156:157] op_sel_hi:[1,0]
	v_pk_mul_f32 v[114:115], v[114:115], v[156:157] op_sel_hi:[1,0]
	v_pk_mul_f32 v[104:105], v[104:105], v[156:157] op_sel_hi:[1,0]
	v_pk_mul_f32 v[106:107], v[106:107], v[156:157] op_sel_hi:[1,0]
	v_pk_mul_f32 v[108:109], v[108:109], v[156:157] op_sel_hi:[1,0]
	v_pk_mul_f32 v[110:111], v[110:111], v[156:157] op_sel_hi:[1,0]
	v_pk_mul_f32 v[100:101], v[100:101], v[156:157] op_sel_hi:[1,0]
	v_pk_mul_f32 v[102:103], v[102:103], v[156:157] op_sel_hi:[1,0]
	v_mul_f32_e32 v108, v112, v108
	v_mul_f32_e32 v109, v113, v109
	v_mul_f32_e32 v110, v114, v110
	v_mul_f32_e32 v111, v115, v111
	v_mul_f32_e32 v100, v104, v100
	v_mul_f32_e32 v101, v105, v101
	v_mul_f32_e32 v102, v106, v102
	v_mul_f32_e32 v103, v107, v103
	v_mul_f32_e32 v112, 0xbfb8aa3b, v112
	v_mul_f32_e32 v113, 0xbfb8aa3b, v113
	v_mul_f32_e32 v114, 0xbfb8aa3b, v114
	v_mul_f32_e32 v115, 0xbfb8aa3b, v115
	v_mul_f32_e32 v104, 0xbfb8aa3b, v104
	v_mul_f32_e32 v105, 0xbfb8aa3b, v105
	v_mul_f32_e32 v106, 0xbfb8aa3b, v106
	v_mul_f32_e32 v107, 0xbfb8aa3b, v107
	v_exp_f32_e32 v112, v112
	v_exp_f32_e32 v113, v113
	v_exp_f32_e32 v114, v114
	v_exp_f32_e32 v115, v115
	v_exp_f32_e32 v104, v104
	v_exp_f32_e32 v105, v105
	v_exp_f32_e32 v106, v106
	v_exp_f32_e32 v107, v107
	v_add_f32_e32 v112, 1.0, v112
	v_add_f32_e32 v113, 1.0, v113
	v_add_f32_e32 v114, 1.0, v114
	v_add_f32_e32 v115, 1.0, v115
	v_add_f32_e32 v104, 1.0, v104
	v_add_f32_e32 v105, 1.0, v105
	v_add_f32_e32 v106, 1.0, v106
	v_add_f32_e32 v107, 1.0, v107
	v_rcp_f32_e32 v112, v112
	v_rcp_f32_e32 v113, v113
	v_rcp_f32_e32 v114, v114
	v_rcp_f32_e32 v115, v115
	v_rcp_f32_e32 v104, v104
	v_rcp_f32_e32 v105, v105
	v_rcp_f32_e32 v106, v106
	v_rcp_f32_e32 v107, v107
	v_mul_f32_e32 v112, v108, v112
	v_mul_f32_e32 v113, v109, v113
	v_mul_f32_e32 v114, v110, v114
	v_mul_f32_e32 v115, v111, v115
	v_mul_f32_e32 v104, v100, v104
	v_mul_f32_e32 v105, v101, v105
	v_mul_f32_e32 v106, v102, v106
	v_mul_f32_e32 v107, v103, v107
	v_cvt_pk_bf16_f32 v112, v112, v113
	v_cvt_pk_bf16_f32 v113, v114, v115
	v_cvt_pk_bf16_f32 v114, v104, v105
	v_cvt_pk_bf16_f32 v115, v106, v107
	global_store_dwordx4 v185, v[112:115], s[28:29]
	v_pk_mul_f32 v[96:97], v[96:97], v[160:161] op_sel_hi:[1,0]
	v_pk_mul_f32 v[98:99], v[98:99], v[160:161] op_sel_hi:[1,0]
	v_pk_mul_f32 v[88:89], v[88:89], v[160:161] op_sel_hi:[1,0]
	v_pk_mul_f32 v[90:91], v[90:91], v[160:161] op_sel_hi:[1,0]
	v_pk_mul_f32 v[92:93], v[92:93], v[160:161] op_sel_hi:[1,0]
	v_pk_mul_f32 v[94:95], v[94:95], v[160:161] op_sel_hi:[1,0]
	v_pk_mul_f32 v[84:85], v[84:85], v[160:161] op_sel_hi:[1,0]
	v_pk_mul_f32 v[86:87], v[86:87], v[160:161] op_sel_hi:[1,0]
	v_mul_f32_e32 v92, v96, v92
	v_mul_f32_e32 v93, v97, v93
	v_mul_f32_e32 v94, v98, v94
	v_mul_f32_e32 v95, v99, v95
	v_mul_f32_e32 v84, v88, v84
	v_mul_f32_e32 v85, v89, v85
	v_mul_f32_e32 v86, v90, v86
	v_mul_f32_e32 v87, v91, v87
	v_mul_f32_e32 v96, 0xbfb8aa3b, v96
	v_mul_f32_e32 v97, 0xbfb8aa3b, v97
	v_mul_f32_e32 v98, 0xbfb8aa3b, v98
	v_mul_f32_e32 v99, 0xbfb8aa3b, v99
	v_mul_f32_e32 v88, 0xbfb8aa3b, v88
	v_mul_f32_e32 v89, 0xbfb8aa3b, v89
	v_mul_f32_e32 v90, 0xbfb8aa3b, v90
	v_mul_f32_e32 v91, 0xbfb8aa3b, v91
	v_exp_f32_e32 v96, v96
	v_exp_f32_e32 v97, v97
	v_exp_f32_e32 v98, v98
	v_exp_f32_e32 v99, v99
	v_exp_f32_e32 v88, v88
	v_exp_f32_e32 v89, v89
	v_exp_f32_e32 v90, v90
	v_exp_f32_e32 v91, v91
	v_add_f32_e32 v96, 1.0, v96
	v_add_f32_e32 v97, 1.0, v97
	v_add_f32_e32 v98, 1.0, v98
	v_add_f32_e32 v99, 1.0, v99
	v_add_f32_e32 v88, 1.0, v88
	v_add_f32_e32 v89, 1.0, v89
	v_add_f32_e32 v90, 1.0, v90
	v_add_f32_e32 v91, 1.0, v91
	v_rcp_f32_e32 v96, v96
	v_rcp_f32_e32 v97, v97
	v_rcp_f32_e32 v98, v98
	v_rcp_f32_e32 v99, v99
	v_rcp_f32_e32 v88, v88
	v_rcp_f32_e32 v89, v89
	v_rcp_f32_e32 v90, v90
	v_rcp_f32_e32 v91, v91
	v_mul_f32_e32 v96, v92, v96
	v_mul_f32_e32 v97, v93, v97
	v_mul_f32_e32 v98, v94, v98
	v_mul_f32_e32 v99, v95, v99
	v_mul_f32_e32 v88, v84, v88
	v_mul_f32_e32 v89, v85, v89
	v_mul_f32_e32 v90, v86, v90
	v_mul_f32_e32 v91, v87, v91
	v_cvt_pk_bf16_f32 v96, v96, v97
	v_cvt_pk_bf16_f32 v97, v98, v99
	v_cvt_pk_bf16_f32 v98, v88, v89
	v_cvt_pk_bf16_f32 v99, v90, v91
	global_store_dwordx4 v186, v[96:99], s[28:29]
	v_pk_mul_f32 v[80:81], v[80:81], v[164:165] op_sel_hi:[1,0]
	v_pk_mul_f32 v[82:83], v[82:83], v[164:165] op_sel_hi:[1,0]
	v_pk_mul_f32 v[72:73], v[72:73], v[164:165] op_sel_hi:[1,0]
	v_pk_mul_f32 v[74:75], v[74:75], v[164:165] op_sel_hi:[1,0]
	v_pk_mul_f32 v[76:77], v[76:77], v[164:165] op_sel_hi:[1,0]
	v_pk_mul_f32 v[78:79], v[78:79], v[164:165] op_sel_hi:[1,0]
	v_pk_mul_f32 v[68:69], v[68:69], v[164:165] op_sel_hi:[1,0]
	v_pk_mul_f32 v[70:71], v[70:71], v[164:165] op_sel_hi:[1,0]
	v_mul_f32_e32 v76, v80, v76
	v_mul_f32_e32 v77, v81, v77
	v_mul_f32_e32 v78, v82, v78
	v_mul_f32_e32 v79, v83, v79
	v_mul_f32_e32 v68, v72, v68
	v_mul_f32_e32 v69, v73, v69
	v_mul_f32_e32 v70, v74, v70
	v_mul_f32_e32 v71, v75, v71
	v_mul_f32_e32 v80, 0xbfb8aa3b, v80
	v_mul_f32_e32 v81, 0xbfb8aa3b, v81
; __device__ __forceinline__ unsigned cvt_pk_bf16(float lo, float hi) { unsigned r; asm volatile("v_cvt_pk_bf16_f32 %0, %1, %2" : "=v"(r) : "v"(lo), "v"(hi)); return r; }
;     __device__ __forceinline__ void operator()(const f32x4 (&acc)[2][2][4][2], const Unit& u, int wr, int wc, int fr, int fq) const {
;     ...
;             for (int m = 0; m < 4; ++m) { const int row = row0 + ai * HALF + m * 16; const f32x4 q0 = *(const f32x4*)(ssq + (size_t)row * 16), q1 = *(const f32x4*)(ssq + (size_t)row * 16 + 4), q2 = *(const f32x4*)(ssq + (size_t)row * 16 + 8), q3 = *(const f32x4*)(ssq + (size_t)row * 16 + 12);
;                 const float rs = rsqrtf(((((q0[0] + q0[1]) + (q0[2] + q0[3])) + ((q1[0] + q1[1]) + (q1[2] + q1[3]))) + (((q2[0] + q2[1]) + (q2[2] + q2[3])) + ((q3[0] + q3[1]) + (q3[2] + q3[3])))) * (1.0f / 1024.0f) + 1e-6f);
;                 float a[8];
; #pragma unroll
;                 for (int n = 0; n < 2; ++n)
; #pragma unroll
;                     for (int j = 0; j < 4; ++j) { const float g = acc[ai][0][m][n][j] * rs, up = acc[ai][1][m][n][j] * rs; a[4 * n + j] = g * up * __builtin_amdgcn_rcpf(1.0f + __expf(-g)); }
;                 u32x4 w; w.x = cvt_pk_bf16(a[0], a[1]); w.y = cvt_pk_bf16(a[2], a[3]); w.z = cvt_pk_bf16(a[4], a[5]); w.w = cvt_pk_bf16(a[6], a[7]);
;                 *(u32x4*)(O + (size_t)row * ldc + col0) = w; }
	v_mul_f32_e32 v82, 0xbfb8aa3b, v82
	v_mul_f32_e32 v83, 0xbfb8aa3b, v83
	v_mul_f32_e32 v72, 0xbfb8aa3b, v72
	v_mul_f32_e32 v73, 0xbfb8aa3b, v73
	v_mul_f32_e32 v74, 0xbfb8aa3b, v74
	v_mul_f32_e32 v75, 0xbfb8aa3b, v75
	v_exp_f32_e32 v80, v80
	v_exp_f32_e32 v81, v81
	v_exp_f32_e32 v82, v82
	v_exp_f32_e32 v83, v83
	v_exp_f32_e32 v72, v72
	v_exp_f32_e32 v73, v73
	v_exp_f32_e32 v74, v74
	v_exp_f32_e32 v75, v75
	v_add_f32_e32 v80, 1.0, v80
	v_add_f32_e32 v81, 1.0, v81
	v_add_f32_e32 v82, 1.0, v82
	v_add_f32_e32 v83, 1.0, v83
	v_add_f32_e32 v72, 1.0, v72
	v_add_f32_e32 v73, 1.0, v73
	v_add_f32_e32 v74, 1.0, v74
	v_add_f32_e32 v75, 1.0, v75
	v_rcp_f32_e32 v80, v80
	v_rcp_f32_e32 v81, v81
	v_rcp_f32_e32 v82, v82
	v_rcp_f32_e32 v83, v83
	v_rcp_f32_e32 v72, v72
	v_rcp_f32_e32 v73, v73
	v_rcp_f32_e32 v74, v74
	v_rcp_f32_e32 v75, v75
	v_mul_f32_e32 v80, v76, v80
	v_mul_f32_e32 v81, v77, v81
	v_mul_f32_e32 v82, v78, v82
	v_mul_f32_e32 v83, v79, v83
	v_mul_f32_e32 v72, v68, v72
	v_mul_f32_e32 v73, v69, v73
	v_mul_f32_e32 v74, v70, v74
	v_mul_f32_e32 v75, v71, v75
	v_cvt_pk_bf16_f32 v80, v80, v81
	v_cvt_pk_bf16_f32 v81, v82, v83
	v_cvt_pk_bf16_f32 v82, v72, v73
	v_cvt_pk_bf16_f32 v83, v74, v75
	global_store_dwordx4 v187, v[80:83], s[28:29]
	v_pk_mul_f32 v[64:65], v[64:65], v[168:169] op_sel_hi:[1,0]
	v_pk_mul_f32 v[66:67], v[66:67], v[168:169] op_sel_hi:[1,0]
	v_pk_mul_f32 v[56:57], v[56:57], v[168:169] op_sel_hi:[1,0]
	v_pk_mul_f32 v[58:59], v[58:59], v[168:169] op_sel_hi:[1,0]
	v_pk_mul_f32 v[60:61], v[60:61], v[168:169] op_sel_hi:[1,0]
	v_pk_mul_f32 v[62:63], v[62:63], v[168:169] op_sel_hi:[1,0]
	v_pk_mul_f32 v[52:53], v[52:53], v[168:169] op_sel_hi:[1,0]
	v_pk_mul_f32 v[54:55], v[54:55], v[168:169] op_sel_hi:[1,0]
	v_mul_f32_e32 v60, v64, v60
	v_mul_f32_e32 v61, v65, v61
	v_mul_f32_e32 v62, v66, v62
	v_mul_f32_e32 v63, v67, v63
	v_mul_f32_e32 v52, v56, v52
	v_mul_f32_e32 v53, v57, v53
	v_mul_f32_e32 v54, v58, v54
	v_mul_f32_e32 v55, v59, v55
	v_mul_f32_e32 v64, 0xbfb8aa3b, v64
	v_mul_f32_e32 v65, 0xbfb8aa3b, v65
	v_mul_f32_e32 v66, 0xbfb8aa3b, v66
	v_mul_f32_e32 v67, 0xbfb8aa3b, v67
	v_mul_f32_e32 v56, 0xbfb8aa3b, v56
	v_mul_f32_e32 v57, 0xbfb8aa3b, v57
	v_mul_f32_e32 v58, 0xbfb8aa3b, v58
	v_mul_f32_e32 v59, 0xbfb8aa3b, v59
	v_exp_f32_e32 v64, v64
	v_exp_f32_e32 v65, v65
	v_exp_f32_e32 v66, v66
	v_exp_f32_e32 v67, v67
	v_exp_f32_e32 v56, v56
	v_exp_f32_e32 v57, v57
	v_exp_f32_e32 v58, v58
	v_exp_f32_e32 v59, v59
	v_add_f32_e32 v64, 1.0, v64
	v_add_f32_e32 v65, 1.0, v65
	v_add_f32_e32 v66, 1.0, v66
	v_add_f32_e32 v67, 1.0, v67
	v_add_f32_e32 v56, 1.0, v56
	v_add_f32_e32 v57, 1.0, v57
	v_add_f32_e32 v58, 1.0, v58
	v_add_f32_e32 v59, 1.0, v59
	v_rcp_f32_e32 v64, v64
	v_rcp_f32_e32 v65, v65
	v_rcp_f32_e32 v66, v66
	v_rcp_f32_e32 v67, v67
	v_rcp_f32_e32 v56, v56
	v_rcp_f32_e32 v57, v57
	v_rcp_f32_e32 v58, v58
	v_rcp_f32_e32 v59, v59
	v_mul_f32_e32 v64, v60, v64
	v_mul_f32_e32 v65, v61, v65
	v_mul_f32_e32 v66, v62, v66
	v_mul_f32_e32 v67, v63, v67
	v_mul_f32_e32 v56, v52, v56
	v_mul_f32_e32 v57, v53, v57
	v_mul_f32_e32 v58, v54, v58
	v_mul_f32_e32 v59, v55, v59
	v_cvt_pk_bf16_f32 v64, v64, v65
	v_cvt_pk_bf16_f32 v65, v66, v67
	v_cvt_pk_bf16_f32 v66, v56, v57
	v_cvt_pk_bf16_f32 v67, v58, v59
	global_store_dwordx4 v188, v[64:67], s[28:29]
	v_pk_mul_f32 v[48:49], v[48:49], v[172:173] op_sel_hi:[1,0]
	v_pk_mul_f32 v[50:51], v[50:51], v[172:173] op_sel_hi:[1,0]
	v_pk_mul_f32 v[40:41], v[40:41], v[172:173] op_sel_hi:[1,0]
	v_pk_mul_f32 v[42:43], v[42:43], v[172:173] op_sel_hi:[1,0]
	v_pk_mul_f32 v[44:45], v[44:45], v[172:173] op_sel_hi:[1,0]
	v_pk_mul_f32 v[46:47], v[46:47], v[172:173] op_sel_hi:[1,0]
	v_pk_mul_f32 v[36:37], v[36:37], v[172:173] op_sel_hi:[1,0]
	v_pk_mul_f32 v[38:39], v[38:39], v[172:173] op_sel_hi:[1,0]
	v_mul_f32_e32 v44, v48, v44
	v_mul_f32_e32 v45, v49, v45
	v_mul_f32_e32 v46, v50, v46
	v_mul_f32_e32 v47, v51, v47
	v_mul_f32_e32 v36, v40, v36
	v_mul_f32_e32 v37, v41, v37
	v_mul_f32_e32 v38, v42, v38
	v_mul_f32_e32 v39, v43, v39
	v_mul_f32_e32 v48, 0xbfb8aa3b, v48
	v_mul_f32_e32 v49, 0xbfb8aa3b, v49
	v_mul_f32_e32 v50, 0xbfb8aa3b, v50
	v_mul_f32_e32 v51, 0xbfb8aa3b, v51
	v_mul_f32_e32 v40, 0xbfb8aa3b, v40
	v_mul_f32_e32 v41, 0xbfb8aa3b, v41
	v_mul_f32_e32 v42, 0xbfb8aa3b, v42
	v_mul_f32_e32 v43, 0xbfb8aa3b, v43
	v_exp_f32_e32 v48, v48
	v_exp_f32_e32 v49, v49
	v_exp_f32_e32 v50, v50
	v_exp_f32_e32 v51, v51
	v_exp_f32_e32 v40, v40
	v_exp_f32_e32 v41, v41
	v_exp_f32_e32 v42, v42
	v_exp_f32_e32 v43, v43
	v_add_f32_e32 v48, 1.0, v48
	v_add_f32_e32 v49, 1.0, v49
	v_add_f32_e32 v50, 1.0, v50
	v_add_f32_e32 v51, 1.0, v51
	v_add_f32_e32 v40, 1.0, v40
	v_add_f32_e32 v41, 1.0, v41
	v_add_f32_e32 v42, 1.0, v42
	v_add_f32_e32 v43, 1.0, v43
	v_rcp_f32_e32 v48, v48
	v_rcp_f32_e32 v49, v49
	v_rcp_f32_e32 v50, v50
	v_rcp_f32_e32 v51, v51
	v_rcp_f32_e32 v40, v40
; __device__ __forceinline__ unsigned cvt_pk_bf16(float lo, float hi) { unsigned r; asm volatile("v_cvt_pk_bf16_f32 %0, %1, %2" : "=v"(r) : "v"(lo), "v"(hi)); return r; }
;     __device__ __forceinline__ void operator()(const f32x4 (&acc)[2][2][4][2], const Unit& u, int wr, int wc, int fr, int fq) const {
;     ...
;             for (int m = 0; m < 4; ++m) { const int row = row0 + ai * HALF + m * 16; const f32x4 q0 = *(const f32x4*)(ssq + (size_t)row * 16), q1 = *(const f32x4*)(ssq + (size_t)row * 16 + 4), q2 = *(const f32x4*)(ssq + (size_t)row * 16 + 8), q3 = *(const f32x4*)(ssq + (size_t)row * 16 + 12);
;                 const float rs = rsqrtf(((((q0[0] + q0[1]) + (q0[2] + q0[3])) + ((q1[0] + q1[1]) + (q1[2] + q1[3]))) + (((q2[0] + q2[1]) + (q2[2] + q2[3])) + ((q3[0] + q3[1]) + (q3[2] + q3[3])))) * (1.0f / 1024.0f) + 1e-6f);
;                 float a[8];
; #pragma unroll
;                 for (int n = 0; n < 2; ++n)
; #pragma unroll
;                     for (int j = 0; j < 4; ++j) { const float g = acc[ai][0][m][n][j] * rs, up = acc[ai][1][m][n][j] * rs; a[4 * n + j] = g * up * __builtin_amdgcn_rcpf(1.0f + __expf(-g)); }
;                 u32x4 w; w.x = cvt_pk_bf16(a[0], a[1]); w.y = cvt_pk_bf16(a[2], a[3]); w.z = cvt_pk_bf16(a[4], a[5]); w.w = cvt_pk_bf16(a[6], a[7]);
;                 *(u32x4*)(O + (size_t)row * ldc + col0) = w; }
	v_rcp_f32_e32 v41, v41
	v_rcp_f32_e32 v42, v42
	v_rcp_f32_e32 v43, v43
	v_mul_f32_e32 v48, v44, v48
	v_mul_f32_e32 v49, v45, v49
	v_mul_f32_e32 v50, v46, v50
	v_mul_f32_e32 v51, v47, v51
	v_mul_f32_e32 v40, v36, v40
	v_mul_f32_e32 v41, v37, v41
	v_mul_f32_e32 v42, v38, v42
	v_mul_f32_e32 v43, v39, v43
	v_cvt_pk_bf16_f32 v48, v48, v49
	v_cvt_pk_bf16_f32 v49, v50, v51
	v_cvt_pk_bf16_f32 v50, v40, v41
	v_cvt_pk_bf16_f32 v51, v42, v43
	global_store_dwordx4 v189, v[48:51], s[28:29]
	v_pk_mul_f32 v[32:33], v[32:33], v[176:177] op_sel_hi:[1,0]
	v_pk_mul_f32 v[34:35], v[34:35], v[176:177] op_sel_hi:[1,0]
	v_pk_mul_f32 v[24:25], v[24:25], v[176:177] op_sel_hi:[1,0]
	v_pk_mul_f32 v[26:27], v[26:27], v[176:177] op_sel_hi:[1,0]
	v_pk_mul_f32 v[28:29], v[28:29], v[176:177] op_sel_hi:[1,0]
	v_pk_mul_f32 v[30:31], v[30:31], v[176:177] op_sel_hi:[1,0]
	v_pk_mul_f32 v[20:21], v[20:21], v[176:177] op_sel_hi:[1,0]
	v_pk_mul_f32 v[22:23], v[22:23], v[176:177] op_sel_hi:[1,0]
	v_mul_f32_e32 v28, v32, v28
	v_mul_f32_e32 v29, v33, v29
	v_mul_f32_e32 v30, v34, v30
	v_mul_f32_e32 v31, v35, v31
	v_mul_f32_e32 v20, v24, v20
	v_mul_f32_e32 v21, v25, v21
	v_mul_f32_e32 v22, v26, v22
	v_mul_f32_e32 v23, v27, v23
	v_mul_f32_e32 v32, 0xbfb8aa3b, v32
	v_mul_f32_e32 v33, 0xbfb8aa3b, v33
	v_mul_f32_e32 v34, 0xbfb8aa3b, v34
	v_mul_f32_e32 v35, 0xbfb8aa3b, v35
	v_mul_f32_e32 v24, 0xbfb8aa3b, v24
	v_mul_f32_e32 v25, 0xbfb8aa3b, v25
	v_mul_f32_e32 v26, 0xbfb8aa3b, v26
	v_mul_f32_e32 v27, 0xbfb8aa3b, v27
	v_exp_f32_e32 v32, v32
	v_exp_f32_e32 v33, v33
	v_exp_f32_e32 v34, v34
	v_exp_f32_e32 v35, v35
	v_exp_f32_e32 v24, v24
	v_exp_f32_e32 v25, v25
	v_exp_f32_e32 v26, v26
	v_exp_f32_e32 v27, v27
	v_add_f32_e32 v32, 1.0, v32
	v_add_f32_e32 v33, 1.0, v33
	v_add_f32_e32 v34, 1.0, v34
	v_add_f32_e32 v35, 1.0, v35
	v_add_f32_e32 v24, 1.0, v24
	v_add_f32_e32 v25, 1.0, v25
	v_add_f32_e32 v26, 1.0, v26
	v_add_f32_e32 v27, 1.0, v27
	v_rcp_f32_e32 v32, v32
	v_rcp_f32_e32 v33, v33
	v_rcp_f32_e32 v34, v34
	v_rcp_f32_e32 v35, v35
	v_rcp_f32_e32 v24, v24
	v_rcp_f32_e32 v25, v25
	v_rcp_f32_e32 v26, v26
	v_rcp_f32_e32 v27, v27
	v_mul_f32_e32 v32, v28, v32
	v_mul_f32_e32 v33, v29, v33
	v_mul_f32_e32 v34, v30, v34
	v_mul_f32_e32 v35, v31, v35
	v_mul_f32_e32 v24, v20, v24
	v_mul_f32_e32 v25, v21, v25
	v_mul_f32_e32 v26, v22, v26
	v_mul_f32_e32 v27, v23, v27
	v_cvt_pk_bf16_f32 v32, v32, v33
	v_cvt_pk_bf16_f32 v33, v34, v35
	v_cvt_pk_bf16_f32 v34, v24, v25
	v_cvt_pk_bf16_f32 v35, v26, v27
	global_store_dwordx4 v190, v[32:35], s[28:29]
	v_pk_mul_f32 v[16:17], v[16:17], v[180:181] op_sel_hi:[1,0]
	v_pk_mul_f32 v[18:19], v[18:19], v[180:181] op_sel_hi:[1,0]
	v_pk_mul_f32 v[8:9], v[8:9], v[180:181] op_sel_hi:[1,0]
	v_pk_mul_f32 v[10:11], v[10:11], v[180:181] op_sel_hi:[1,0]
	v_pk_mul_f32 v[12:13], v[12:13], v[180:181] op_sel_hi:[1,0]
	v_pk_mul_f32 v[14:15], v[14:15], v[180:181] op_sel_hi:[1,0]
	v_pk_mul_f32 v[4:5], v[4:5], v[180:181] op_sel_hi:[1,0]
	v_pk_mul_f32 v[6:7], v[6:7], v[180:181] op_sel_hi:[1,0]
	v_mul_f32_e32 v12, v16, v12
	v_mul_f32_e32 v13, v17, v13
	v_mul_f32_e32 v14, v18, v14
	v_mul_f32_e32 v15, v19, v15
	v_mul_f32_e32 v4, v8, v4
	v_mul_f32_e32 v5, v9, v5
	v_mul_f32_e32 v6, v10, v6
	v_mul_f32_e32 v7, v11, v7
	v_mul_f32_e32 v16, 0xbfb8aa3b, v16
	v_mul_f32_e32 v17, 0xbfb8aa3b, v17
	v_mul_f32_e32 v18, 0xbfb8aa3b, v18
	v_mul_f32_e32 v19, 0xbfb8aa3b, v19
	v_mul_f32_e32 v8, 0xbfb8aa3b, v8
	v_mul_f32_e32 v9, 0xbfb8aa3b, v9
	v_mul_f32_e32 v10, 0xbfb8aa3b, v10
	v_mul_f32_e32 v11, 0xbfb8aa3b, v11
	v_exp_f32_e32 v16, v16
	v_exp_f32_e32 v17, v17
	v_exp_f32_e32 v18, v18
	v_exp_f32_e32 v19, v19
	v_exp_f32_e32 v8, v8
	v_exp_f32_e32 v9, v9
	v_exp_f32_e32 v10, v10
	v_exp_f32_e32 v11, v11
	v_add_f32_e32 v16, 1.0, v16
	v_add_f32_e32 v17, 1.0, v17
	v_add_f32_e32 v18, 1.0, v18
	v_add_f32_e32 v19, 1.0, v19
	v_add_f32_e32 v8, 1.0, v8
	v_add_f32_e32 v9, 1.0, v9
	v_add_f32_e32 v10, 1.0, v10
	v_add_f32_e32 v11, 1.0, v11
	v_rcp_f32_e32 v16, v16
	v_rcp_f32_e32 v17, v17
	v_rcp_f32_e32 v18, v18
	v_rcp_f32_e32 v19, v19
	v_rcp_f32_e32 v8, v8
	v_rcp_f32_e32 v9, v9
	v_rcp_f32_e32 v10, v10
	v_rcp_f32_e32 v11, v11
	v_mul_f32_e32 v16, v12, v16
	v_mul_f32_e32 v17, v13, v17
	v_mul_f32_e32 v18, v14, v18
	v_mul_f32_e32 v19, v15, v19
	v_mul_f32_e32 v8, v4, v8
	v_mul_f32_e32 v9, v5, v9
	v_mul_f32_e32 v10, v6, v10
	v_mul_f32_e32 v11, v7, v11
	v_cvt_pk_bf16_f32 v16, v16, v17
	v_cvt_pk_bf16_f32 v17, v18, v19
	v_cvt_pk_bf16_f32 v18, v8, v9
	v_cvt_pk_bf16_f32 v19, v10, v11
	global_store_dwordx4 v191, v[16:19], s[28:29]
	s_mov_b32 s23, 0x800000
	v_readlane_b32 s60, v253, 3
	s_mov_b32 s99, 0x800000
	v_readlane_b32 s61, v253, 4
	v_readlane_b32 s62, v253, 5
	v_readlane_b32 s63, v253, 6
	s_andn2_b64 vcc, exec, s[2:3]
	s_mov_b64 s[28:29], -1
	s_cbranch_vccnz .LBB0_603
	s_andn2_b64 vcc, exec, s[14:15]
	s_cbranch_vccnz .LBB0_602
	s_barrier
	s_branch .LBB0_602
